# placement: loops before the attention phase shifted by 8 bytes, later code unchanged
# speedup vs baseline: 1.0021x; 1.0002x over previous
.LBB0_131:
	s_add_u32 s6, s8, 0x13900000
	s_mul_i32 s72, s14, 0xc000
	s_addc_u32 s7, s9, 0
	s_lshl_b64 s[14:15], s[72:73], 2
	s_add_u32 s8, s8, s14
	s_addc_u32 s9, s9, s15
	s_add_u32 s8, s8, 0x40000
	s_addc_u32 s9, s9, 0
	s_lshl_b32 s12, s12, 5
	s_and_b32 s15, s12, 0x60
	s_add_i32 m0, s27, 0x18000
	v_lshl_add_u64 v[6:7], v[6:7], 0, s[74:75]
	s_lshl_b32 s14, s11, 13
	s_lshl_b32 s18, s15, 7
	s_waitcnt vmcnt(2)
	s_barrier
	global_load_lds_dwordx4 v[6:7], off
	v_lshl_add_u64 v[4:5], v[4:5], 0, s[74:75]
	s_add_i32 m0, s27, 0x1a000
	s_add_i32 s38, s27, 0x8000
	s_add_i32 s39, s27, 0xa000
	global_load_lds_dwordx4 v[4:5], off
	v_lshl_add_u64 v[0:1], v[0:1], 0, s[74:75]
	s_mov_b32 m0, s38
	s_add_u32 s12, s30, 0x80080
	global_load_lds_dwordx4 v[0:1], off
	v_lshl_add_u64 v[0:1], v[2:3], 0, s[74:75]
	s_mov_b32 m0, s39
	s_addc_u32 s13, s31, 0
	global_load_lds_dwordx4 v[0:1], off
	s_add_i32 m0, s27, 0x1c000
	v_lshl_add_u64 v[0:1], s[12:13], 0, v[132:133]
	global_load_lds_dwordx4 v[0:1], off
	v_lshl_add_u64 v[0:1], s[12:13], 0, v[128:129]
	s_add_i32 m0, s27, 0x1e000
	s_cmpk_lt_u32 s10, 0x100
	global_load_lds_dwordx4 v[0:1], off
	v_lshrrev_b32_e32 v0, 1, v8
	v_and_b32_e32 v0, 24, v0
	v_and_b32_e32 v1, 15, v8
	v_lshlrev_b32_e32 v2, 1, v0
	v_lshl_or_b32 v142, s11, 6, v1
	v_lshl_or_b32 v1, v1, 6, v2
	v_lshlrev_b32_e32 v2, 2, v8
	v_and_b32_e32 v2, 32, v2
	v_bitop3_b32 v3, v1, s14, v2 bitop3:0xde
	v_bitop3_b32 v143, v1, s18, v2 bitop3:0xde
	v_lshlrev_b32_e32 v1, 15, v13
	v_and_b32_e32 v1, 0xffff0000, v1
	v_lshl_add_u32 v1, v12, 12, v1
	v_and_b32_e32 v2, 1, v13
	v_lshl_or_b32 v1, v2, 6, v1
	v_lshl_add_u32 v136, v14, 1, v1
	v_lshlrev_b32_e32 v1, 15, v9
	v_and_b32_e32 v1, 0xffff0000, v1
	s_waitcnt vmcnt(6)
	v_lshl_add_u32 v1, v10, 12, v1
	v_and_b32_e32 v2, 1, v9
	v_lshl_or_b32 v1, v2, 6, v1
	v_readlane_b32 s12, v254, 20
	s_cselect_b64 s[10:11], -1, 0
	v_mov_b32_e32 v137, v177
	v_lshl_add_u32 v138, v11, 1, v1
	v_mov_b32_e32 v139, v177
	s_mov_b32 s40, 0
	v_add_u32_e32 v144, 0, v3
	s_lshl_b32 s72, s15, 1
	v_lshlrev_b32_e32 v176, 1, v0
	v_readlane_b32 s41, v254, 19
	s_mov_b32 s42, s12
	s_barrier
	v_readlane_b32 s13, v254, 21
	s_branch .LBB0_134
	s_nop 0
	s_nop 0

.LBB0_581:
	s_cmp_lt_u32 s3, 0x400001
	s_mov_b64 s[24:25], 0
	s_cselect_b64 s[28:29], -1, 0
	s_and_b64 vcc, exec, s[28:29]
	s_cbranch_vccz .LBB0_575
	s_branch .LBB0_580
	s_nop 0
	s_nop 0
	s_nop 0
	s_nop 0
	s_nop 0
	s_nop 0
	s_nop 0
	s_nop 0
	s_nop 0
	s_nop 0
	s_nop 0
	s_nop 0
	s_nop 0
	s_nop 0
